# v23 + isel bit refinement: one key row of every pair counted on the scalar unit (v_cmp to SGPR pair, s_bcnt1) instead of a second VALU carry add
# speedup vs baseline: 1.0017x; 1.0017x over previous
.LBB0_492:
	v_lshlrev_b32_e64 v67, v2, 1
	v_or_b32_e32 v67, v67, v3
	s_andn2_b64 vcc, exec, s[30:31]
	v_mov_b32_e32 v68, 0
	s_mov_b32 s100, 0
	s_cbranch_vccz .LBB0_503
	s_and_b64 vcc, exec, s[0:1]
	s_cbranch_vccz .LBB0_504

.LBB0_500:
	v_cmp_ge_u32_e64 s[98:99], v60, v67
	v_cmp_ge_u32_e32 vcc, v62, v67
	s_bcnt1_i32_b64 s98, s[98:99]
	s_add_i32 s100, s100, s98
	v_addc_co_u32_e32 v68, vcc, 0, v68, vcc
	v_cmp_ge_u32_e64 s[98:99], v64, v67
	v_cmp_ge_u32_e32 vcc, v66, v67
	s_bcnt1_i32_b64 s98, s[98:99]
	s_add_i32 s100, s100, s98
	v_addc_co_u32_e32 v68, vcc, 0, v68, vcc
	v_cmp_ge_u32_e64 s[98:99], v59, v67
	v_cmp_ge_u32_e32 vcc, v61, v67
	s_bcnt1_i32_b64 s98, s[98:99]
	s_add_i32 s100, s100, s98
	v_addc_co_u32_e32 v68, vcc, 0, v68, vcc
	v_cmp_ge_u32_e64 s[98:99], v63, v67
	v_cmp_ge_u32_e32 vcc, v65, v67
	s_bcnt1_i32_b64 s98, s[98:99]
	s_add_i32 s100, s100, s98
	v_addc_co_u32_e32 v68, vcc, 0, v68, vcc
.LBB0_501:
	v_and_b32_e32 v69, 1, v68
	v_cmp_ne_u32_e32 vcc, 0, v69
	v_bfe_u32 v69, v68, 1, 1
	s_bcnt1_i32_b64 s16, vcc
	v_cmp_ne_u32_e32 vcc, 0, v69
	s_bcnt1_i32_b64 s17, vcc
	v_bfe_u32 v69, v68, 2, 1
	s_lshl_b32 s17, s17, 1
	v_cmp_ne_u32_e32 vcc, 0, v69
	s_add_i32 s16, s17, s16
	s_bcnt1_i32_b64 s17, vcc
	v_bfe_u32 v69, v68, 3, 1
	s_lshl_b32 s17, s17, 2
	v_cmp_ne_u32_e32 vcc, 0, v69
	s_add_i32 s16, s16, s17
	s_bcnt1_i32_b64 s17, vcc
	v_bfe_u32 v69, v68, 4, 1
	s_lshl_b32 s17, s17, 3
	v_cmp_ne_u32_e32 vcc, 0, v69
	s_add_i32 s16, s16, s17
	s_bcnt1_i32_b64 s17, vcc
	v_bfe_u32 v69, v68, 5, 1
	s_lshl_b32 s17, s17, 4
	v_cmp_ne_u32_e32 vcc, 0, v69
	s_add_i32 s16, s16, s17
	s_bcnt1_i32_b64 s17, vcc
	v_bfe_u32 v68, v68, 6, 1
	s_lshl_b32 s17, s17, 5
	v_cmp_ne_u32_e32 vcc, 0, v68
	s_add_i32 s18, s16, s17
	s_bcnt1_i32_b64 s16, vcc
	s_lshl_b32 s16, s16, 6
	s_add_i32 s18, s18, s16
	s_add_i32 s18, s18, s100
	s_cmpk_lt_u32 s18, 0x100
	s_mov_b64 s[16:17], 0
	s_cbranch_scc1 .LBB0_510
	s_cmpk_eq_i32 s18, 0x100
	s_cselect_b64 s[16:17], -1, 0
	s_or_b64 s[2:3], s[16:17], s[2:3]
	v_subrev_co_u32_e32 v2, vcc, 1, v2
	s_or_b64 s[16:17], s[16:17], vcc
	s_andn2_b64 vcc, exec, s[16:17]
	s_cbranch_vccnz .LBB0_511
	s_branch .LBB0_513
.LBB0_503:
	v_cmp_ge_u32_e64 s[98:99], v0, v67
	v_cmp_ge_u32_e32 vcc, v4, v67
	s_bcnt1_i32_b64 s98, s[98:99]
	s_add_i32 s100, s100, s98
	v_addc_co_u32_e32 v68, vcc, 0, v68, vcc
	v_cmp_ge_u32_e64 s[98:99], v6, v67
	v_cmp_ge_u32_e32 vcc, v5, v67
	s_bcnt1_i32_b64 s98, s[98:99]
	s_add_i32 s100, s100, s98
	v_addc_co_u32_e32 v68, vcc, 0, v68, vcc
	v_cmp_ge_u32_e64 s[98:99], v8, v67
	v_cmp_ge_u32_e32 vcc, v7, v67
	s_bcnt1_i32_b64 s98, s[98:99]
	s_add_i32 s100, s100, s98
	v_addc_co_u32_e32 v68, vcc, 0, v68, vcc
	v_cmp_ge_u32_e64 s[98:99], v10, v67
	v_cmp_ge_u32_e32 vcc, v9, v67
	s_bcnt1_i32_b64 s98, s[98:99]
	s_add_i32 s100, s100, s98
	v_addc_co_u32_e32 v68, vcc, 0, v68, vcc
	s_and_b64 vcc, exec, s[0:1]
	s_cbranch_vccnz .LBB0_494
.LBB0_504:
	v_cmp_ge_u32_e64 s[98:99], v12, v67
	v_cmp_ge_u32_e32 vcc, v14, v67
	s_bcnt1_i32_b64 s98, s[98:99]
	s_add_i32 s100, s100, s98
	v_addc_co_u32_e32 v68, vcc, 0, v68, vcc
	v_cmp_ge_u32_e64 s[98:99], v16, v67
	v_cmp_ge_u32_e32 vcc, v18, v67
	s_bcnt1_i32_b64 s98, s[98:99]
	s_add_i32 s100, s100, s98
	v_addc_co_u32_e32 v68, vcc, 0, v68, vcc
	v_cmp_ge_u32_e64 s[98:99], v11, v67
	v_cmp_ge_u32_e32 vcc, v13, v67
	s_bcnt1_i32_b64 s98, s[98:99]
	s_add_i32 s100, s100, s98
	v_addc_co_u32_e32 v68, vcc, 0, v68, vcc
	v_cmp_ge_u32_e64 s[98:99], v15, v67
	v_cmp_ge_u32_e32 vcc, v17, v67
	s_bcnt1_i32_b64 s98, s[98:99]
	s_add_i32 s100, s100, s98
	v_addc_co_u32_e32 v68, vcc, 0, v68, vcc
	s_and_b64 vcc, exec, s[14:15]
	s_cbranch_vccnz .LBB0_495
.LBB0_505:
	v_cmp_ge_u32_e64 s[98:99], v20, v67
	v_cmp_ge_u32_e32 vcc, v22, v67
	s_bcnt1_i32_b64 s98, s[98:99]
	s_add_i32 s100, s100, s98
	v_addc_co_u32_e32 v68, vcc, 0, v68, vcc
	v_cmp_ge_u32_e64 s[98:99], v24, v67
	v_cmp_ge_u32_e32 vcc, v26, v67
	s_bcnt1_i32_b64 s98, s[98:99]
	s_add_i32 s100, s100, s98
	v_addc_co_u32_e32 v68, vcc, 0, v68, vcc
	v_cmp_ge_u32_e64 s[98:99], v19, v67
	v_cmp_ge_u32_e32 vcc, v21, v67
	s_bcnt1_i32_b64 s98, s[98:99]
	s_add_i32 s100, s100, s98
	v_addc_co_u32_e32 v68, vcc, 0, v68, vcc
	v_cmp_ge_u32_e64 s[98:99], v23, v67
	v_cmp_ge_u32_e32 vcc, v25, v67
	s_bcnt1_i32_b64 s98, s[98:99]
	s_add_i32 s100, s100, s98
	v_addc_co_u32_e32 v68, vcc, 0, v68, vcc
	s_and_b64 vcc, exec, s[4:5]
	s_cbranch_vccnz .LBB0_496
.LBB0_506:
	v_cmp_ge_u32_e64 s[98:99], v28, v67
	v_cmp_ge_u32_e32 vcc, v30, v67
	s_bcnt1_i32_b64 s98, s[98:99]
	s_add_i32 s100, s100, s98
	v_addc_co_u32_e32 v68, vcc, 0, v68, vcc
	v_cmp_ge_u32_e64 s[98:99], v32, v67
	v_cmp_ge_u32_e32 vcc, v34, v67
	s_bcnt1_i32_b64 s98, s[98:99]
	s_add_i32 s100, s100, s98
	v_addc_co_u32_e32 v68, vcc, 0, v68, vcc
	v_cmp_ge_u32_e64 s[98:99], v27, v67
	v_cmp_ge_u32_e32 vcc, v29, v67
	s_bcnt1_i32_b64 s98, s[98:99]
	s_add_i32 s100, s100, s98
	v_addc_co_u32_e32 v68, vcc, 0, v68, vcc
	v_cmp_ge_u32_e64 s[98:99], v31, v67
	v_cmp_ge_u32_e32 vcc, v33, v67
	s_bcnt1_i32_b64 s98, s[98:99]
	s_add_i32 s100, s100, s98
	v_addc_co_u32_e32 v68, vcc, 0, v68, vcc
	s_and_b64 vcc, exec, s[6:7]
	s_cbranch_vccnz .LBB0_497
.LBB0_507:
	v_cmp_ge_u32_e64 s[98:99], v36, v67
	v_cmp_ge_u32_e32 vcc, v38, v67
	s_bcnt1_i32_b64 s98, s[98:99]
	s_add_i32 s100, s100, s98
	v_addc_co_u32_e32 v68, vcc, 0, v68, vcc
	v_cmp_ge_u32_e64 s[98:99], v40, v67
	v_cmp_ge_u32_e32 vcc, v42, v67
	s_bcnt1_i32_b64 s98, s[98:99]
	s_add_i32 s100, s100, s98
	v_addc_co_u32_e32 v68, vcc, 0, v68, vcc
	v_cmp_ge_u32_e64 s[98:99], v35, v67
	v_cmp_ge_u32_e32 vcc, v37, v67
	s_bcnt1_i32_b64 s98, s[98:99]
	s_add_i32 s100, s100, s98
	v_addc_co_u32_e32 v68, vcc, 0, v68, vcc
	v_cmp_ge_u32_e64 s[98:99], v39, v67
	v_cmp_ge_u32_e32 vcc, v41, v67
	s_bcnt1_i32_b64 s98, s[98:99]
	s_add_i32 s100, s100, s98
	v_addc_co_u32_e32 v68, vcc, 0, v68, vcc
	s_and_b64 vcc, exec, s[8:9]
	s_cbranch_vccnz .LBB0_498
.LBB0_508:
	v_cmp_ge_u32_e64 s[98:99], v44, v67
	v_cmp_ge_u32_e32 vcc, v46, v67
	s_bcnt1_i32_b64 s98, s[98:99]
	s_add_i32 s100, s100, s98
	v_addc_co_u32_e32 v68, vcc, 0, v68, vcc
	v_cmp_ge_u32_e64 s[98:99], v48, v67
	v_cmp_ge_u32_e32 vcc, v50, v67
	s_bcnt1_i32_b64 s98, s[98:99]
	s_add_i32 s100, s100, s98
	v_addc_co_u32_e32 v68, vcc, 0, v68, vcc
	v_cmp_ge_u32_e64 s[98:99], v43, v67
	v_cmp_ge_u32_e32 vcc, v45, v67
	s_bcnt1_i32_b64 s98, s[98:99]
	s_add_i32 s100, s100, s98
	v_addc_co_u32_e32 v68, vcc, 0, v68, vcc
	v_cmp_ge_u32_e64 s[98:99], v47, v67
	v_cmp_ge_u32_e32 vcc, v49, v67
	s_bcnt1_i32_b64 s98, s[98:99]
	s_add_i32 s100, s100, s98
	v_addc_co_u32_e32 v68, vcc, 0, v68, vcc
	s_and_b64 vcc, exec, s[10:11]
	s_cbranch_vccnz .LBB0_499
.LBB0_509:
	v_cmp_ge_u32_e64 s[98:99], v52, v67
	v_cmp_ge_u32_e32 vcc, v54, v67
	s_bcnt1_i32_b64 s98, s[98:99]
	s_add_i32 s100, s100, s98
	v_addc_co_u32_e32 v68, vcc, 0, v68, vcc
	v_cmp_ge_u32_e64 s[98:99], v56, v67
	v_cmp_ge_u32_e32 vcc, v58, v67
	s_bcnt1_i32_b64 s98, s[98:99]
	s_add_i32 s100, s100, s98
	v_addc_co_u32_e32 v68, vcc, 0, v68, vcc
	v_cmp_ge_u32_e64 s[98:99], v51, v67
	v_cmp_ge_u32_e32 vcc, v53, v67
	s_bcnt1_i32_b64 s98, s[98:99]
	s_add_i32 s100, s100, s98
	v_addc_co_u32_e32 v68, vcc, 0, v68, vcc
	v_cmp_ge_u32_e64 s[98:99], v55, v67
	v_cmp_ge_u32_e32 vcc, v57, v67
	s_bcnt1_i32_b64 s98, s[98:99]
	s_add_i32 s100, s100, s98
	v_addc_co_u32_e32 v68, vcc, 0, v68, vcc
	s_and_b64 vcc, exec, s[12:13]
	s_cbranch_vccz .LBB0_500
	s_branch .LBB0_501
